# EpiResid: second-half residual loads hoisted next to first-half loads (one wait for 16 loads, no wait on stores)
# speedup vs baseline: 1.0190x; 1.0038x over previous
; #define LAS __attribute__((address_space(3)))
; __device__ __forceinline__ unsigned cvt_pk_bf16(float lo, float hi) { unsigned r; asm volatile("v_cvt_pk_bf16_f32 %0, %1, %2" : "=v"(r) : "v"(lo), "v"(hi)); return r; }
; __device__ __forceinline__ float bf_lo(unsigned w) { return __uint_as_float(w << 16); }
; __device__ __forceinline__ float bf_hi(unsigned w) { return __uint_as_float(w & 0xffff0000u); }
;     __device__ __forceinline__ void operator()(Acc& acc, const Unit& u, int wr, int wc, int fr, int fq, LAS unsigned char*, const LAS float* rst) const {
;         const int row0 = u.pm * 256 + wr * 64 + fr, col0 = u.pn * 256 + wc * 32 + 8 * fq;
; #pragma unroll
;         for (int ai = 0; ai < 2; ++ai) {
;             u32x4 xo[4][2];
; #pragma unroll
;             for (int m = 0; m < 4; ++m) { const size_t off = (size_t)(row0 + ai * 128 + m * 16) * D + col0;
; #pragma unroll
;                 for (int bj = 0; bj < 2; ++bj) xo[m][bj] = *(const u32x4*)(XB + off + bj * 128); }
;             asm volatile("" ::: "memory");
; #pragma unroll
;             for (int m = 0; m < 4; ++m) {
;                 const int row = row0 + ai * 128 + m * 16; const size_t off = (size_t)row * D + col0; float s = 0.f;
; #pragma unroll
;                 for (int bj = 0; bj < 2; ++bj) { const f32x4 a0 = acc[ai][bj][m][0], a1 = acc[ai][bj][m][1]; const u32x4 o = xo[m][bj];
;                     const float n0 = bf_lo(o.x) + a0[0] * scale, n1 = bf_hi(o.x) + a0[1] * scale, n2 = bf_lo(o.y) + a0[2] * scale, n3 = bf_hi(o.y) + a0[3] * scale;
;                     const float n4 = bf_lo(o.z) + a1[0] * scale, n5 = bf_hi(o.z) + a1[1] * scale, n6 = bf_lo(o.w) + a1[2] * scale, n7 = bf_hi(o.w) + a1[3] * scale;
;                     u32x4 w; w.x = cvt_pk_bf16(n0, n1); w.y = cvt_pk_bf16(n2, n3); w.z = cvt_pk_bf16(n4, n5); w.w = cvt_pk_bf16(n6, n7); *(u32x4*)(XB + off + bj * 128) = w;
;                     s += ((n0 * n0 + n1 * n1) + (n2 * n2 + n3 * n3)) + ((n4 * n4 + n5 * n5) + (n6 * n6 + n7 * n7)); }
;                 s += __shfl_xor(s, 16); s += __shfl_xor(s, 32);
;                 if (fq == 0) ssq[(size_t)row * 16 + u.pn * 4 + wc] = s;
.LBB0_730:
	v_lshl_or_b32 v166, s10, 8, v193
	v_lshl_add_u32 v170, s18, 8, v191
	v_ashrrev_i32_e32 v167, 31, v166
	v_lshlrev_b64 v[204:205], 1, v[166:167]
	v_ashrrev_i32_e32 v171, 31, v170
	v_lshl_add_u64 v[168:169], s[14:15], 0, v[204:205]
	v_lshlrev_b64 v[206:207], 11, v[170:171]
	v_lshl_add_u64 v[114:115], v[168:169], 0, v[206:207]
	global_load_dwordx4 v[196:199], v[114:115], off
	global_load_dwordx4 v[200:203], v[114:115], off offset:256
	v_or_b32_e32 v180, 16, v170
	v_ashrrev_i32_e32 v181, 31, v180
	v_or_b32_e32 v176, 32, v170
	v_lshlrev_b64 v[182:183], 11, v[180:181]
	v_ashrrev_i32_e32 v177, 31, v176
	v_or_b32_e32 v172, 48, v170
	v_lshl_add_u64 v[114:115], v[168:169], 0, v[182:183]
	v_lshlrev_b64 v[178:179], 11, v[176:177]
	v_ashrrev_i32_e32 v173, 31, v172
	global_load_dwordx4 v[134:137], v[114:115], off
	global_load_dwordx4 v[130:133], v[114:115], off offset:256
	v_lshl_add_u64 v[114:115], v[168:169], 0, v[178:179]
	v_lshlrev_b64 v[174:175], 11, v[172:173]
	global_load_dwordx4 v[126:129], v[114:115], off
	global_load_dwordx4 v[122:125], v[114:115], off offset:256
	v_lshl_add_u64 v[114:115], v[168:169], 0, v[174:175]
	global_load_dwordx4 v[118:121], v[114:115], off
	s_nop 0
	global_load_dwordx4 v[114:117], v[114:115], off offset:256
	s_lshl_b32 s42, s10, 2
	s_ashr_i32 s43, s42, 31
	v_add_u32_e32 v240, 0x80, v170
	v_ashrrev_i32_e32 v241, 31, v240
	v_lshlrev_b64 v[240:241], 11, v[240:241]
	v_lshl_add_u64 v[242:243], v[168:169], 0, v[240:241]
	global_load_dwordx4 v[208:211], v[242:243], off
	global_load_dwordx4 v[212:215], v[242:243], off offset:256
	v_add_u32_e32 v240, 0x90, v170
	v_ashrrev_i32_e32 v241, 31, v240
	v_lshlrev_b64 v[240:241], 11, v[240:241]
	v_lshl_add_u64 v[242:243], v[168:169], 0, v[240:241]
	global_load_dwordx4 v[216:219], v[242:243], off
	global_load_dwordx4 v[220:223], v[242:243], off offset:256
	v_add_u32_e32 v240, 0xa0, v170
	v_ashrrev_i32_e32 v241, 31, v240
	v_lshlrev_b64 v[240:241], 11, v[240:241]
	v_lshl_add_u64 v[242:243], v[168:169], 0, v[240:241]
	global_load_dwordx4 v[224:227], v[242:243], off
	global_load_dwordx4 v[228:231], v[242:243], off offset:256
	v_add_u32_e32 v240, 0xb0, v170
	v_ashrrev_i32_e32 v241, 31, v240
	v_lshlrev_b64 v[240:241], 11, v[240:241]
	v_lshl_add_u64 v[242:243], v[168:169], 0, v[240:241]
	global_load_dwordx4 v[232:235], v[242:243], off
	global_load_dwordx4 v[236:239], v[242:243], off offset:256
	s_waitcnt vmcnt(0) lgkmcnt(0)
	v_lshlrev_b32_e32 v190, 16, v196
	v_and_b32_e32 v195, 0xffff0000, v196
	v_lshlrev_b32_e32 v196, 16, v197
	v_fmac_f32_e32 v196, s2, v152
	v_and_b32_e32 v152, 0xffff0000, v197
	v_fmac_f32_e32 v190, s2, v150
	v_fmac_f32_e32 v195, s2, v151
	v_fmac_f32_e32 v152, s2, v153
	v_lshlrev_b32_e32 v153, 16, v198
	v_and_b32_e32 v197, 0xffff0000, v198
	v_lshl_add_u64 v[150:151], s[14:15], 0, v[206:207]
	v_fmac_f32_e32 v153, s2, v146
	v_fmac_f32_e32 v197, s2, v147
	v_lshlrev_b32_e32 v198, 16, v199
	v_and_b32_e32 v199, 0xffff0000, v199
	v_cvt_pk_bf16_f32 v146, v190, v195
	v_cvt_pk_bf16_f32 v147, v196, v152
	v_lshl_add_u64 v[150:151], v[150:151], 0, v[204:205]
	v_fmac_f32_e32 v198, s2, v148
	v_fmac_f32_e32 v199, s2, v149
	v_cvt_pk_bf16_f32 v148, v153, v197
	v_cvt_pk_bf16_f32 v149, v198, v199
	global_store_dwordx4 v[150:151], v[146:149], off
	s_nop 1
	v_mul_f32_e32 v146, v195, v195
	v_mul_f32_e32 v147, v152, v152
	v_fmac_f32_e32 v146, v190, v190
	v_fmac_f32_e32 v147, v196, v196
	v_add_f32_e32 v146, v146, v147
	v_mul_f32_e32 v147, v197, v197
	v_mul_f32_e32 v148, v199, v199
	v_fmac_f32_e32 v147, v153, v153
	v_fmac_f32_e32 v148, v198, v198
	v_add_f32_e32 v147, v147, v148
	v_add_f32_e32 v146, v146, v147
	v_lshlrev_b32_e32 v147, 16, v200
	v_fmac_f32_e32 v147, s2, v142
	v_and_b32_e32 v142, 0xffff0000, v200
	v_fmac_f32_e32 v142, s2, v143
	v_lshlrev_b32_e32 v143, 16, v201
	v_fmac_f32_e32 v143, s2, v144
	v_and_b32_e32 v144, 0xffff0000, v201
	v_fmac_f32_e32 v144, s2, v145
	v_lshlrev_b32_e32 v145, 16, v202
	v_and_b32_e32 v148, 0xffff0000, v202
	v_fmac_f32_e32 v145, s2, v138
	v_fmac_f32_e32 v148, s2, v139
	v_lshlrev_b32_e32 v149, 16, v203
	v_and_b32_e32 v152, 0xffff0000, v203
	v_cvt_pk_bf16_f32 v138, v147, v142
	v_cvt_pk_bf16_f32 v139, v143, v144
	v_fmac_f32_e32 v149, s2, v140
	v_fmac_f32_e32 v152, s2, v141
	v_cvt_pk_bf16_f32 v140, v145, v148
	v_cvt_pk_bf16_f32 v141, v149, v152
	global_store_dwordx4 v[150:151], v[138:141], off offset:256
	s_nop 1
	v_mul_f32_e32 v138, v142, v142
	v_mul_f32_e32 v139, v144, v144
	v_fmac_f32_e32 v138, v147, v147
	v_fmac_f32_e32 v139, v143, v143
	v_add_f32_e32 v138, v138, v139
	v_mul_f32_e32 v139, v148, v148
	v_mul_f32_e32 v140, v152, v152
	v_fmac_f32_e32 v139, v145, v145
	v_fmac_f32_e32 v140, v149, v149
	v_add_f32_e32 v139, v139, v140
	v_add_f32_e32 v138, v138, v139
	v_and_b32_e32 v140, 64, v185
	v_add_f32_e32 v139, v146, v138
	v_xor_b32_e32 v138, 16, v185
	v_add_u32_e32 v141, 64, v140
	v_cmp_lt_i32_e32 vcc, v138, v141
	s_nop 1
	v_cndmask_b32_e32 v138, v185, v138, vcc
	v_lshlrev_b32_e32 v138, 2, v138
	ds_bpermute_b32 v140, v138, v139
	s_waitcnt lgkmcnt(0)
	v_add_f32_e32 v140, v139, v140
	v_xor_b32_e32 v139, 32, v185
	v_cmp_lt_i32_e32 vcc, v139, v141
	s_nop 1
	v_cndmask_b32_e32 v139, v185, v139, vcc
	v_lshlrev_b32_e32 v139, 2, v139
	ds_bpermute_b32 v141, v139, v140
	s_and_saveexec_b64 s[10:11], s[0:1]
	s_cbranch_execz .LBB0_732
	v_lshlrev_b64 v[142:143], 6, v[170:171]
	v_lshl_add_u64 v[142:143], s[12:13], 0, v[142:143]
	v_lshl_add_u64 v[142:143], s[42:43], 2, v[142:143]
	s_lshl_b32 s46, s95, 2
	v_lshl_add_u64 v[142:143], v[142:143], 0, s[46:47]
	s_waitcnt lgkmcnt(0)
	v_add_f32_e32 v140, v140, v141
	global_store_dword v[142:143], v140, off
; __device__ __forceinline__ unsigned cvt_pk_bf16(float lo, float hi) { unsigned r; asm volatile("v_cvt_pk_bf16_f32 %0, %1, %2" : "=v"(r) : "v"(lo), "v"(hi)); return r; }
; __device__ __forceinline__ float bf_lo(unsigned w) { return __uint_as_float(w << 16); }
; __device__ __forceinline__ float bf_hi(unsigned w) { return __uint_as_float(w & 0xffff0000u); }
;     __device__ __forceinline__ void operator()(Acc& acc, const Unit& u, int wr, int wc, int fr, int fq, LAS unsigned char*, const LAS float* rst) const {
;     ...
;             for (int m = 0; m < 4; ++m) {
;                 const int row = row0 + ai * 128 + m * 16; const size_t off = (size_t)row * D + col0; float s = 0.f;
; #pragma unroll
;                 for (int bj = 0; bj < 2; ++bj) { const f32x4 a0 = acc[ai][bj][m][0], a1 = acc[ai][bj][m][1]; const u32x4 o = xo[m][bj];
;                     const float n0 = bf_lo(o.x) + a0[0] * scale, n1 = bf_hi(o.x) + a0[1] * scale, n2 = bf_lo(o.y) + a0[2] * scale, n3 = bf_hi(o.y) + a0[3] * scale;
;                     const float n4 = bf_lo(o.z) + a1[0] * scale, n5 = bf_hi(o.z) + a1[1] * scale, n6 = bf_lo(o.w) + a1[2] * scale, n7 = bf_hi(o.w) + a1[3] * scale;
;                     u32x4 w; w.x = cvt_pk_bf16(n0, n1); w.y = cvt_pk_bf16(n2, n3); w.z = cvt_pk_bf16(n4, n5); w.w = cvt_pk_bf16(n6, n7); *(u32x4*)(XB + off + bj * 128) = w;
;                     s += ((n0 * n0 + n1 * n1) + (n2 * n2 + n3 * n3)) + ((n4 * n4 + n5 * n5) + (n6 * n6 + n7 * n7)); }
;                 s += __shfl_xor(s, 16); s += __shfl_xor(s, 32);
;                 if (fq == 0) ssq[(size_t)row * 16 + u.pn * 4 + wc] = s;
.LBB0_732:
	s_or_b64 exec, exec, s[10:11]
	v_lshlrev_b32_e32 v140, 16, v134
	v_fmac_f32_e32 v140, s2, v110
	v_and_b32_e32 v110, 0xffff0000, v134
	v_fmac_f32_e32 v110, s2, v111
	v_lshlrev_b32_e32 v111, 16, v135
	v_fmac_f32_e32 v111, s2, v112
	v_and_b32_e32 v112, 0xffff0000, v135
	v_fmac_f32_e32 v112, s2, v113
	v_lshlrev_b32_e32 v113, 16, v136
	v_and_b32_e32 v134, 0xffff0000, v136
	v_fmac_f32_e32 v113, s2, v106
	v_fmac_f32_e32 v134, s2, v107
	v_and_b32_e32 v136, 0xffff0000, v137
	v_cvt_pk_bf16_f32 v106, v140, v110
	v_cvt_pk_bf16_f32 v107, v111, v112
	v_mul_f32_e32 v110, v110, v110
	v_mul_f32_e32 v112, v112, v112
	v_lshlrev_b32_e32 v135, 16, v137
	v_fmac_f32_e32 v136, s2, v109
	v_fmac_f32_e32 v110, v140, v140
	v_fmac_f32_e32 v112, v111, v111
	v_fmac_f32_e32 v135, s2, v108
	v_add_f32_e32 v110, v110, v112
	v_mul_f32_e32 v111, v134, v134
	v_mul_f32_e32 v112, v136, v136
	v_fmac_f32_e32 v111, v113, v113
	v_fmac_f32_e32 v112, v135, v135
	v_add_f32_e32 v111, v111, v112
	v_add_f32_e32 v110, v110, v111
	v_lshlrev_b32_e32 v111, 16, v130
	v_fmac_f32_e32 v111, s2, v102
	v_and_b32_e32 v102, 0xffff0000, v130
	v_and_b32_e32 v112, 0xffff0000, v131
	v_cvt_pk_bf16_f32 v108, v113, v134
	v_fmac_f32_e32 v102, s2, v103
	v_lshlrev_b32_e32 v103, 16, v131
	v_fmac_f32_e32 v112, s2, v105
	v_lshlrev_b32_e32 v113, 16, v132
	v_and_b32_e32 v130, 0xffff0000, v132
	v_fmac_f32_e32 v103, s2, v104
	v_fmac_f32_e32 v113, s2, v98
	v_fmac_f32_e32 v130, s2, v99
	v_and_b32_e32 v132, 0xffff0000, v133
	v_mul_f32_e32 v98, v102, v102
	v_mul_f32_e32 v99, v112, v112
	v_lshlrev_b32_e32 v131, 16, v133
	v_fmac_f32_e32 v132, s2, v101
	v_fmac_f32_e32 v98, v111, v111
	v_fmac_f32_e32 v99, v103, v103
	v_fmac_f32_e32 v131, s2, v100
	v_add_f32_e32 v98, v98, v99
	v_mul_f32_e32 v99, v130, v130
	v_mul_f32_e32 v100, v132, v132
	v_fmac_f32_e32 v99, v113, v113
	v_fmac_f32_e32 v100, v131, v131
	v_add_f32_e32 v99, v99, v100
	v_add_f32_e32 v98, v98, v99
	v_add_f32_e32 v101, v110, v98
	ds_bpermute_b32 v110, v138, v101
	v_lshl_add_u64 v[98:99], s[14:15], 0, v[182:183]
	v_lshl_add_u64 v[104:105], v[166:167], 1, v[98:99]
	v_cvt_pk_bf16_f32 v109, v135, v136
	global_store_dwordx4 v[104:105], v[106:109], off
	s_waitcnt lgkmcnt(0)
	v_add_f32_e32 v98, v101, v110
	ds_bpermute_b32 v99, v139, v98
	v_cvt_pk_bf16_f32 v100, v111, v102
	v_cvt_pk_bf16_f32 v101, v103, v112
	v_cvt_pk_bf16_f32 v102, v113, v130
	v_cvt_pk_bf16_f32 v103, v131, v132
	global_store_dwordx4 v[104:105], v[100:103], off offset:256
	s_and_saveexec_b64 s[10:11], s[0:1]
	s_cbranch_execz .LBB0_734
	v_lshlrev_b64 v[100:101], 6, v[180:181]
	v_lshl_add_u64 v[100:101], s[12:13], 0, v[100:101]
	v_lshl_add_u64 v[100:101], s[42:43], 2, v[100:101]
	s_lshl_b32 s46, s95, 2
	v_lshl_add_u64 v[100:101], v[100:101], 0, s[46:47]
	s_waitcnt lgkmcnt(0)
	v_add_f32_e32 v98, v98, v99
	global_store_dword v[100:101], v98, off
.LBB0_734:
	s_or_b64 exec, exec, s[10:11]
	v_lshlrev_b32_e32 v98, 16, v126
	v_fmac_f32_e32 v98, s2, v94
	v_and_b32_e32 v94, 0xffff0000, v126
	v_fmac_f32_e32 v94, s2, v95
	v_lshlrev_b32_e32 v95, 16, v127
	v_fmac_f32_e32 v95, s2, v96
	v_and_b32_e32 v96, 0xffff0000, v127
	v_fmac_f32_e32 v96, s2, v97
	v_lshlrev_b32_e32 v97, 16, v128
	s_waitcnt lgkmcnt(0)
	v_and_b32_e32 v99, 0xffff0000, v128
	v_fmac_f32_e32 v97, s2, v90
	v_fmac_f32_e32 v99, s2, v91
	v_and_b32_e32 v101, 0xffff0000, v129
	v_cvt_pk_bf16_f32 v90, v98, v94
	v_cvt_pk_bf16_f32 v91, v95, v96
	v_mul_f32_e32 v94, v94, v94
	v_mul_f32_e32 v96, v96, v96
	v_lshlrev_b32_e32 v100, 16, v129
	v_fmac_f32_e32 v101, s2, v93
	v_fmac_f32_e32 v94, v98, v98
	v_fmac_f32_e32 v96, v95, v95
	v_fmac_f32_e32 v100, s2, v92
	v_add_f32_e32 v94, v94, v96
	v_mul_f32_e32 v95, v99, v99
	v_mul_f32_e32 v96, v101, v101
	v_fmac_f32_e32 v95, v97, v97
	v_fmac_f32_e32 v96, v100, v100
	v_add_f32_e32 v95, v95, v96
	v_add_f32_e32 v94, v94, v95
	v_lshlrev_b32_e32 v95, 16, v122
	v_fmac_f32_e32 v95, s2, v86
	v_and_b32_e32 v86, 0xffff0000, v122
	v_and_b32_e32 v96, 0xffff0000, v123
	v_cvt_pk_bf16_f32 v92, v97, v99
	v_fmac_f32_e32 v86, s2, v87
	v_lshlrev_b32_e32 v87, 16, v123
	v_fmac_f32_e32 v96, s2, v89
	v_lshlrev_b32_e32 v97, 16, v124
	v_and_b32_e32 v98, 0xffff0000, v124
	v_cvt_pk_bf16_f32 v93, v100, v101
	v_fmac_f32_e32 v87, s2, v88
	v_fmac_f32_e32 v97, s2, v82
	v_fmac_f32_e32 v98, s2, v83
	v_and_b32_e32 v100, 0xffff0000, v125
	v_mul_f32_e32 v82, v86, v86
	v_mul_f32_e32 v83, v96, v96
	v_lshlrev_b32_e32 v99, 16, v125
	v_fmac_f32_e32 v100, s2, v85
	v_fmac_f32_e32 v82, v95, v95
	v_fmac_f32_e32 v83, v87, v87
	v_fmac_f32_e32 v99, s2, v84
	v_add_f32_e32 v82, v82, v83
	v_mul_f32_e32 v83, v98, v98
	v_mul_f32_e32 v84, v100, v100
	v_fmac_f32_e32 v83, v97, v97
	v_fmac_f32_e32 v84, v99, v99
	v_add_f32_e32 v83, v83, v84
	v_add_f32_e32 v82, v82, v83
	v_add_f32_e32 v85, v94, v82
	ds_bpermute_b32 v94, v138, v85
	v_lshl_add_u64 v[82:83], s[14:15], 0, v[178:179]
	v_lshl_add_u64 v[88:89], v[166:167], 1, v[82:83]
	global_store_dwordx4 v[88:89], v[90:93], off
	v_cvt_pk_bf16_f32 v84, v95, v86
	s_waitcnt lgkmcnt(0)
	v_add_f32_e32 v82, v85, v94
	ds_bpermute_b32 v83, v139, v82
	v_cvt_pk_bf16_f32 v85, v87, v96
	v_cvt_pk_bf16_f32 v86, v97, v98
	v_cvt_pk_bf16_f32 v87, v99, v100
	global_store_dwordx4 v[88:89], v[84:87], off offset:256
	s_and_saveexec_b64 s[10:11], s[0:1]
	s_cbranch_execz .LBB0_736
	v_lshlrev_b64 v[84:85], 6, v[176:177]
	v_lshl_add_u64 v[84:85], s[12:13], 0, v[84:85]
	v_lshl_add_u64 v[84:85], s[42:43], 2, v[84:85]
	s_lshl_b32 s46, s95, 2
	v_lshl_add_u64 v[84:85], v[84:85], 0, s[46:47]
	s_waitcnt lgkmcnt(0)
	v_add_f32_e32 v82, v82, v83
	global_store_dword v[84:85], v82, off
; __device__ __forceinline__ unsigned cvt_pk_bf16(float lo, float hi) { unsigned r; asm volatile("v_cvt_pk_bf16_f32 %0, %1, %2" : "=v"(r) : "v"(lo), "v"(hi)); return r; }
; __device__ __forceinline__ float bf_lo(unsigned w) { return __uint_as_float(w << 16); }
; __device__ __forceinline__ float bf_hi(unsigned w) { return __uint_as_float(w & 0xffff0000u); }
;     __device__ __forceinline__ void operator()(Acc& acc, const Unit& u, int wr, int wc, int fr, int fq, LAS unsigned char*, const LAS float* rst) const {
;     ...
;         for (int ai = 0; ai < 2; ++ai) {
;             u32x4 xo[4][2];
; #pragma unroll
;             for (int m = 0; m < 4; ++m) { const size_t off = (size_t)(row0 + ai * 128 + m * 16) * D + col0;
; #pragma unroll
;                 for (int bj = 0; bj < 2; ++bj) xo[m][bj] = *(const u32x4*)(XB + off + bj * 128); }
;             asm volatile("" ::: "memory");
; #pragma unroll
;             for (int m = 0; m < 4; ++m) {
;                 const int row = row0 + ai * 128 + m * 16; const size_t off = (size_t)row * D + col0; float s = 0.f;
; #pragma unroll
;                 for (int bj = 0; bj < 2; ++bj) { const f32x4 a0 = acc[ai][bj][m][0], a1 = acc[ai][bj][m][1]; const u32x4 o = xo[m][bj];
;                     const float n0 = bf_lo(o.x) + a0[0] * scale, n1 = bf_hi(o.x) + a0[1] * scale, n2 = bf_lo(o.y) + a0[2] * scale, n3 = bf_hi(o.y) + a0[3] * scale;
;                     const float n4 = bf_lo(o.z) + a1[0] * scale, n5 = bf_hi(o.z) + a1[1] * scale, n6 = bf_lo(o.w) + a1[2] * scale, n7 = bf_hi(o.w) + a1[3] * scale;
;                     u32x4 w; w.x = cvt_pk_bf16(n0, n1); w.y = cvt_pk_bf16(n2, n3); w.z = cvt_pk_bf16(n4, n5); w.w = cvt_pk_bf16(n6, n7); *(u32x4*)(XB + off + bj * 128) = w;
;                     s += ((n0 * n0 + n1 * n1) + (n2 * n2 + n3 * n3)) + ((n4 * n4 + n5 * n5) + (n6 * n6 + n7 * n7)); }
;                 s += __shfl_xor(s, 16); s += __shfl_xor(s, 32);
;                 if (fq == 0) ssq[(size_t)row * 16 + u.pn * 4 + wc] = s;
.LBB0_736:
	s_or_b64 exec, exec, s[10:11]
	v_lshlrev_b32_e32 v82, 16, v118
	v_fmac_f32_e32 v82, s2, v78
	v_and_b32_e32 v78, 0xffff0000, v118
	v_fmac_f32_e32 v78, s2, v79
	v_lshlrev_b32_e32 v79, 16, v119
	v_fmac_f32_e32 v79, s2, v80
	v_and_b32_e32 v80, 0xffff0000, v119
	v_fmac_f32_e32 v80, s2, v81
	v_lshlrev_b32_e32 v81, 16, v120
	s_waitcnt lgkmcnt(0)
	v_and_b32_e32 v83, 0xffff0000, v120
	v_fmac_f32_e32 v81, s2, v74
	v_fmac_f32_e32 v83, s2, v75
	v_and_b32_e32 v85, 0xffff0000, v121
	v_cvt_pk_bf16_f32 v74, v82, v78
	v_cvt_pk_bf16_f32 v75, v79, v80
	v_mul_f32_e32 v78, v78, v78
	v_mul_f32_e32 v80, v80, v80
	v_lshlrev_b32_e32 v84, 16, v121
	v_fmac_f32_e32 v85, s2, v77
	v_fmac_f32_e32 v78, v82, v82
	v_fmac_f32_e32 v80, v79, v79
	v_fmac_f32_e32 v84, s2, v76
	v_add_f32_e32 v78, v78, v80
	v_mul_f32_e32 v79, v83, v83
	v_mul_f32_e32 v80, v85, v85
	v_fmac_f32_e32 v79, v81, v81
	v_fmac_f32_e32 v80, v84, v84
	v_add_f32_e32 v79, v79, v80
	v_add_f32_e32 v78, v78, v79
	v_lshlrev_b32_e32 v79, 16, v114
	v_fmac_f32_e32 v79, s2, v70
	v_and_b32_e32 v70, 0xffff0000, v114
	v_and_b32_e32 v80, 0xffff0000, v115
	v_cvt_pk_bf16_f32 v76, v81, v83
	v_fmac_f32_e32 v70, s2, v71
	v_lshlrev_b32_e32 v71, 16, v115
	v_fmac_f32_e32 v80, s2, v73
	v_lshlrev_b32_e32 v81, 16, v116
	v_and_b32_e32 v82, 0xffff0000, v116
	v_cvt_pk_bf16_f32 v77, v84, v85
	v_fmac_f32_e32 v71, s2, v72
	v_fmac_f32_e32 v81, s2, v66
	v_fmac_f32_e32 v82, s2, v67
	v_and_b32_e32 v84, 0xffff0000, v117
	v_mul_f32_e32 v66, v70, v70
	v_mul_f32_e32 v67, v80, v80
	v_lshlrev_b32_e32 v83, 16, v117
	v_fmac_f32_e32 v84, s2, v69
	v_fmac_f32_e32 v66, v79, v79
	v_fmac_f32_e32 v67, v71, v71
	v_fmac_f32_e32 v83, s2, v68
	v_add_f32_e32 v66, v66, v67
	v_mul_f32_e32 v67, v82, v82
	v_mul_f32_e32 v68, v84, v84
	v_fmac_f32_e32 v67, v81, v81
	v_fmac_f32_e32 v68, v83, v83
	v_add_f32_e32 v67, v67, v68
	v_add_f32_e32 v66, v66, v67
	v_add_f32_e32 v69, v78, v66
	ds_bpermute_b32 v78, v138, v69
	v_lshl_add_u64 v[66:67], s[14:15], 0, v[174:175]
	v_lshl_add_u64 v[72:73], v[166:167], 1, v[66:67]
	global_store_dwordx4 v[72:73], v[74:77], off
	v_cvt_pk_bf16_f32 v68, v79, v70
	s_waitcnt lgkmcnt(0)
	v_add_f32_e32 v66, v69, v78
	ds_bpermute_b32 v67, v139, v66
	v_cvt_pk_bf16_f32 v69, v71, v80
	v_cvt_pk_bf16_f32 v70, v81, v82
	v_cvt_pk_bf16_f32 v71, v83, v84
	global_store_dwordx4 v[72:73], v[68:71], off offset:256
	s_and_saveexec_b64 s[10:11], s[0:1]
	s_cbranch_execz .LBB0_738
	v_lshlrev_b64 v[68:69], 6, v[172:173]
	v_lshl_add_u64 v[68:69], s[12:13], 0, v[68:69]
	v_lshl_add_u64 v[68:69], s[42:43], 2, v[68:69]
	s_lshl_b32 s46, s95, 2
	v_lshl_add_u64 v[68:69], v[68:69], 0, s[46:47]
	s_waitcnt lgkmcnt(0)
	v_add_f32_e32 v66, v66, v67
	global_store_dword v[68:69], v66, off
.LBB0_738:
	s_or_b64 exec, exec, s[10:11]
	v_add_u32_e32 v106, 0x80, v170
	v_ashrrev_i32_e32 v107, 31, v106
	v_lshlrev_b64 v[112:113], 11, v[106:107]
	s_waitcnt lgkmcnt(0)
	v_lshl_add_u64 v[66:67], v[168:169], 0, v[112:113]
	v_mov_b32_e32 v108, v208
	v_mov_b32_e32 v109, v209
	v_mov_b32_e32 v110, v210
	v_mov_b32_e32 v111, v211
	v_mov_b32_e32 v90, v212
	v_mov_b32_e32 v91, v213
	v_mov_b32_e32 v92, v214
	v_mov_b32_e32 v93, v215
	v_add_u32_e32 v102, 0x90, v170
	v_ashrrev_i32_e32 v103, 31, v102
	v_add_u32_e32 v96, 0xa0, v170
	v_lshlrev_b64 v[104:105], 11, v[102:103]
	v_ashrrev_i32_e32 v97, 31, v96
	v_add_u32_e32 v94, 0xb0, v170
	v_lshl_add_u64 v[66:67], v[168:169], 0, v[104:105]
	v_lshlrev_b64 v[100:101], 11, v[96:97]
	v_ashrrev_i32_e32 v95, 31, v94
	v_mov_b32_e32 v86, v216
	v_mov_b32_e32 v87, v217
	v_mov_b32_e32 v88, v218
	v_mov_b32_e32 v89, v219
	v_mov_b32_e32 v82, v220
	v_mov_b32_e32 v83, v221
	v_mov_b32_e32 v84, v222
	v_mov_b32_e32 v85, v223
	v_lshl_add_u64 v[66:67], v[168:169], 0, v[100:101]
	v_lshlrev_b64 v[98:99], 11, v[94:95]
	v_mov_b32_e32 v78, v224
	v_mov_b32_e32 v79, v225
	v_mov_b32_e32 v80, v226
	v_mov_b32_e32 v81, v227
	v_mov_b32_e32 v74, v228
	v_mov_b32_e32 v75, v229
	v_mov_b32_e32 v76, v230
	v_mov_b32_e32 v77, v231
	v_lshl_add_u64 v[66:67], v[168:169], 0, v[98:99]
	v_mov_b32_e32 v70, v232
	v_mov_b32_e32 v71, v233
	v_mov_b32_e32 v72, v234
	v_mov_b32_e32 v73, v235
	s_nop 0
	v_mov_b32_e32 v66, v236
	v_mov_b32_e32 v67, v237
	v_mov_b32_e32 v68, v238
	v_mov_b32_e32 v69, v239
	s_waitcnt lgkmcnt(0)
	v_lshlrev_b32_e32 v115, 16, v109
	v_lshlrev_b32_e32 v114, 16, v108
	v_and_b32_e32 v108, 0xffff0000, v108
	v_fmac_f32_e32 v115, s2, v64
	v_and_b32_e32 v64, 0xffff0000, v109
	v_fmac_f32_e32 v114, s2, v62
	v_fmac_f32_e32 v108, s2, v63
	v_fmac_f32_e32 v64, s2, v65
	v_lshlrev_b32_e32 v65, 16, v110
	v_and_b32_e32 v109, 0xffff0000, v110
	v_lshl_add_u64 v[62:63], s[14:15], 0, v[112:113]
	v_fmac_f32_e32 v65, s2, v58
	v_fmac_f32_e32 v109, s2, v59
	v_lshlrev_b32_e32 v110, 16, v111
	v_and_b32_e32 v111, 0xffff0000, v111
	v_cvt_pk_bf16_f32 v58, v114, v108
	v_cvt_pk_bf16_f32 v59, v115, v64
	v_lshl_add_u64 v[62:63], v[166:167], 1, v[62:63]
	v_fmac_f32_e32 v110, s2, v60
	v_fmac_f32_e32 v111, s2, v61
	v_cvt_pk_bf16_f32 v60, v65, v109
	v_cvt_pk_bf16_f32 v61, v110, v111
	global_store_dwordx4 v[62:63], v[58:61], off
	s_nop 1
	v_mul_f32_e32 v58, v108, v108
	v_mul_f32_e32 v59, v64, v64
	v_fmac_f32_e32 v58, v114, v114
	v_fmac_f32_e32 v59, v115, v115
	v_add_f32_e32 v58, v58, v59
	v_mul_f32_e32 v59, v109, v109
	v_mul_f32_e32 v60, v111, v111
	v_fmac_f32_e32 v59, v65, v65
	v_fmac_f32_e32 v60, v110, v110
	v_add_f32_e32 v59, v59, v60
	v_add_f32_e32 v58, v58, v59
	v_lshlrev_b32_e32 v59, 16, v90
	v_fmac_f32_e32 v59, s2, v54
	v_and_b32_e32 v54, 0xffff0000, v90
	v_fmac_f32_e32 v54, s2, v55
	v_lshlrev_b32_e32 v55, 16, v91
	v_fmac_f32_e32 v55, s2, v56
	v_and_b32_e32 v56, 0xffff0000, v91
	v_fmac_f32_e32 v56, s2, v57
	v_lshlrev_b32_e32 v57, 16, v92
	v_and_b32_e32 v60, 0xffff0000, v92
	v_fmac_f32_e32 v57, s2, v50
	v_fmac_f32_e32 v60, s2, v51
	v_lshlrev_b32_e32 v61, 16, v93
	v_and_b32_e32 v64, 0xffff0000, v93
	v_cvt_pk_bf16_f32 v50, v59, v54
	v_cvt_pk_bf16_f32 v51, v55, v56
	v_fmac_f32_e32 v61, s2, v52
	v_fmac_f32_e32 v64, s2, v53
	v_cvt_pk_bf16_f32 v52, v57, v60
	v_cvt_pk_bf16_f32 v53, v61, v64
	global_store_dwordx4 v[62:63], v[50:53], off offset:256
	s_nop 1
	v_mul_f32_e32 v50, v54, v54
	v_mul_f32_e32 v51, v56, v56
	v_fmac_f32_e32 v50, v59, v59
	v_fmac_f32_e32 v51, v55, v55
	v_add_f32_e32 v50, v50, v51
	v_mul_f32_e32 v51, v60, v60
	v_mul_f32_e32 v52, v64, v64
	v_fmac_f32_e32 v51, v57, v57
	v_fmac_f32_e32 v52, v61, v61
	v_add_f32_e32 v51, v51, v52
	v_add_f32_e32 v50, v50, v51
	v_add_f32_e32 v50, v58, v50
	ds_bpermute_b32 v51, v138, v50
	s_waitcnt lgkmcnt(0)
	v_add_f32_e32 v50, v50, v51
	ds_bpermute_b32 v51, v139, v50
	s_and_saveexec_b64 s[10:11], s[0:1]
	s_cbranch_execz .LBB0_740
	v_lshlrev_b64 v[52:53], 6, v[106:107]
	v_lshl_add_u64 v[52:53], s[12:13], 0, v[52:53]
	v_lshl_add_u64 v[52:53], s[42:43], 2, v[52:53]
	s_lshl_b32 s46, s95, 2
	v_lshl_add_u64 v[52:53], v[52:53], 0, s[46:47]
	s_waitcnt lgkmcnt(0)
	v_add_f32_e32 v50, v50, v51
	global_store_dword v[52:53], v50, off
; __device__ __forceinline__ unsigned cvt_pk_bf16(float lo, float hi) { unsigned r; asm volatile("v_cvt_pk_bf16_f32 %0, %1, %2" : "=v"(r) : "v"(lo), "v"(hi)); return r; }
; __device__ __forceinline__ float bf_lo(unsigned w) { return __uint_as_float(w << 16); }
; __device__ __forceinline__ float bf_hi(unsigned w) { return __uint_as_float(w & 0xffff0000u); }
;     __device__ __forceinline__ void operator()(Acc& acc, const Unit& u, int wr, int wc, int fr, int fq, LAS unsigned char*, const LAS float* rst) const {
;     ...
;             for (int m = 0; m < 4; ++m) {
;                 const int row = row0 + ai * 128 + m * 16; const size_t off = (size_t)row * D + col0; float s = 0.f;
; #pragma unroll
;                 for (int bj = 0; bj < 2; ++bj) { const f32x4 a0 = acc[ai][bj][m][0], a1 = acc[ai][bj][m][1]; const u32x4 o = xo[m][bj];
;                     const float n0 = bf_lo(o.x) + a0[0] * scale, n1 = bf_hi(o.x) + a0[1] * scale, n2 = bf_lo(o.y) + a0[2] * scale, n3 = bf_hi(o.y) + a0[3] * scale;
;                     const float n4 = bf_lo(o.z) + a1[0] * scale, n5 = bf_hi(o.z) + a1[1] * scale, n6 = bf_lo(o.w) + a1[2] * scale, n7 = bf_hi(o.w) + a1[3] * scale;
;                     u32x4 w; w.x = cvt_pk_bf16(n0, n1); w.y = cvt_pk_bf16(n2, n3); w.z = cvt_pk_bf16(n4, n5); w.w = cvt_pk_bf16(n6, n7); *(u32x4*)(XB + off + bj * 128) = w;
;                     s += ((n0 * n0 + n1 * n1) + (n2 * n2 + n3 * n3)) + ((n4 * n4 + n5 * n5) + (n6 * n6 + n7 * n7)); }
;                 s += __shfl_xor(s, 16); s += __shfl_xor(s, 32);
;                 if (fq == 0) ssq[(size_t)row * 16 + u.pn * 4 + wc] = s;
.LBB0_740:
	s_or_b64 exec, exec, s[10:11]
	v_lshlrev_b32_e32 v50, 16, v86
	v_fmac_f32_e32 v50, s2, v46
	v_and_b32_e32 v46, 0xffff0000, v86
	v_fmac_f32_e32 v46, s2, v47
	v_lshlrev_b32_e32 v47, 16, v87
	v_fmac_f32_e32 v47, s2, v48
	v_and_b32_e32 v48, 0xffff0000, v87
	v_fmac_f32_e32 v48, s2, v49
	v_lshlrev_b32_e32 v49, 16, v88
	s_waitcnt lgkmcnt(0)
	v_and_b32_e32 v51, 0xffff0000, v88
	v_fmac_f32_e32 v49, s2, v42
	v_fmac_f32_e32 v51, s2, v43
	v_and_b32_e32 v53, 0xffff0000, v89
	v_cvt_pk_bf16_f32 v42, v50, v46
	v_cvt_pk_bf16_f32 v43, v47, v48
	v_mul_f32_e32 v46, v46, v46
	v_mul_f32_e32 v48, v48, v48
	v_lshlrev_b32_e32 v52, 16, v89
	v_fmac_f32_e32 v53, s2, v45
	v_fmac_f32_e32 v46, v50, v50
	v_fmac_f32_e32 v48, v47, v47
	v_fmac_f32_e32 v52, s2, v44
	v_add_f32_e32 v46, v46, v48
	v_mul_f32_e32 v47, v51, v51
	v_mul_f32_e32 v48, v53, v53
	v_fmac_f32_e32 v47, v49, v49
	v_fmac_f32_e32 v48, v52, v52
	v_add_f32_e32 v47, v47, v48
	v_add_f32_e32 v46, v46, v47
	v_lshlrev_b32_e32 v47, 16, v82
	v_fmac_f32_e32 v47, s2, v38
	v_and_b32_e32 v38, 0xffff0000, v82
	v_and_b32_e32 v48, 0xffff0000, v83
	v_cvt_pk_bf16_f32 v44, v49, v51
	v_fmac_f32_e32 v38, s2, v39
	v_lshlrev_b32_e32 v39, 16, v83
	v_fmac_f32_e32 v48, s2, v41
	v_lshlrev_b32_e32 v49, 16, v84
	v_and_b32_e32 v50, 0xffff0000, v84
	v_cvt_pk_bf16_f32 v45, v52, v53
	v_fmac_f32_e32 v39, s2, v40
	v_fmac_f32_e32 v49, s2, v34
	v_fmac_f32_e32 v50, s2, v35
	v_and_b32_e32 v52, 0xffff0000, v85
	v_mul_f32_e32 v34, v38, v38
	v_mul_f32_e32 v35, v48, v48
	v_lshlrev_b32_e32 v51, 16, v85
	v_fmac_f32_e32 v52, s2, v37
	v_fmac_f32_e32 v34, v47, v47
	v_fmac_f32_e32 v35, v39, v39
	v_fmac_f32_e32 v51, s2, v36
	v_add_f32_e32 v34, v34, v35
	v_mul_f32_e32 v35, v50, v50
	v_mul_f32_e32 v36, v52, v52
	v_fmac_f32_e32 v35, v49, v49
	v_fmac_f32_e32 v36, v51, v51
	v_add_f32_e32 v35, v35, v36
	v_add_f32_e32 v34, v34, v35
	v_add_f32_e32 v37, v46, v34
	ds_bpermute_b32 v46, v138, v37
	v_lshl_add_u64 v[34:35], s[14:15], 0, v[104:105]
	v_lshl_add_u64 v[40:41], v[166:167], 1, v[34:35]
	global_store_dwordx4 v[40:41], v[42:45], off
	v_cvt_pk_bf16_f32 v36, v47, v38
	s_waitcnt lgkmcnt(0)
	v_add_f32_e32 v34, v37, v46
	ds_bpermute_b32 v35, v139, v34
	v_cvt_pk_bf16_f32 v37, v39, v48
	v_cvt_pk_bf16_f32 v38, v49, v50
	v_cvt_pk_bf16_f32 v39, v51, v52
	global_store_dwordx4 v[40:41], v[36:39], off offset:256
	s_and_saveexec_b64 s[10:11], s[0:1]
	s_cbranch_execz .LBB0_742
	v_lshlrev_b64 v[36:37], 6, v[102:103]
	v_lshl_add_u64 v[36:37], s[12:13], 0, v[36:37]
	v_lshl_add_u64 v[36:37], s[42:43], 2, v[36:37]
	s_lshl_b32 s46, s95, 2
	v_lshl_add_u64 v[36:37], v[36:37], 0, s[46:47]
	s_waitcnt lgkmcnt(0)
	v_add_f32_e32 v34, v34, v35
	global_store_dword v[36:37], v34, off
; __device__ __forceinline__ unsigned cvt_pk_bf16(float lo, float hi) { unsigned r; asm volatile("v_cvt_pk_bf16_f32 %0, %1, %2" : "=v"(r) : "v"(lo), "v"(hi)); return r; }
; __device__ __forceinline__ float bf_lo(unsigned w) { return __uint_as_float(w << 16); }
; __device__ __forceinline__ float bf_hi(unsigned w) { return __uint_as_float(w & 0xffff0000u); }
;     __device__ __forceinline__ void operator()(Acc& acc, const Unit& u, int wr, int wc, int fr, int fq, LAS unsigned char*, const LAS float* rst) const {
;     ...
;             for (int m = 0; m < 4; ++m) {
;                 const int row = row0 + ai * 128 + m * 16; const size_t off = (size_t)row * D + col0; float s = 0.f;
; #pragma unroll
;                 for (int bj = 0; bj < 2; ++bj) { const f32x4 a0 = acc[ai][bj][m][0], a1 = acc[ai][bj][m][1]; const u32x4 o = xo[m][bj];
;                     const float n0 = bf_lo(o.x) + a0[0] * scale, n1 = bf_hi(o.x) + a0[1] * scale, n2 = bf_lo(o.y) + a0[2] * scale, n3 = bf_hi(o.y) + a0[3] * scale;
;                     const float n4 = bf_lo(o.z) + a1[0] * scale, n5 = bf_hi(o.z) + a1[1] * scale, n6 = bf_lo(o.w) + a1[2] * scale, n7 = bf_hi(o.w) + a1[3] * scale;
;                     u32x4 w; w.x = cvt_pk_bf16(n0, n1); w.y = cvt_pk_bf16(n2, n3); w.z = cvt_pk_bf16(n4, n5); w.w = cvt_pk_bf16(n6, n7); *(u32x4*)(XB + off + bj * 128) = w;
;                     s += ((n0 * n0 + n1 * n1) + (n2 * n2 + n3 * n3)) + ((n4 * n4 + n5 * n5) + (n6 * n6 + n7 * n7)); }
;                 s += __shfl_xor(s, 16); s += __shfl_xor(s, 32);
;                 if (fq == 0) ssq[(size_t)row * 16 + u.pn * 4 + wc] = s;
.LBB0_742:
	s_or_b64 exec, exec, s[10:11]
	v_lshlrev_b32_e32 v34, 16, v78
	v_fmac_f32_e32 v34, s2, v30
	v_and_b32_e32 v30, 0xffff0000, v78
	v_fmac_f32_e32 v30, s2, v31
	v_lshlrev_b32_e32 v31, 16, v79
	v_fmac_f32_e32 v31, s2, v32
	v_and_b32_e32 v32, 0xffff0000, v79
	v_fmac_f32_e32 v32, s2, v33
	v_lshlrev_b32_e32 v33, 16, v80
	s_waitcnt lgkmcnt(0)
	v_and_b32_e32 v35, 0xffff0000, v80
	v_fmac_f32_e32 v33, s2, v26
	v_fmac_f32_e32 v35, s2, v27
	v_and_b32_e32 v37, 0xffff0000, v81
	v_cvt_pk_bf16_f32 v26, v34, v30
	v_cvt_pk_bf16_f32 v27, v31, v32
	v_mul_f32_e32 v30, v30, v30
	v_mul_f32_e32 v32, v32, v32
	v_lshlrev_b32_e32 v36, 16, v81
	v_fmac_f32_e32 v37, s2, v29
	v_fmac_f32_e32 v30, v34, v34
	v_fmac_f32_e32 v32, v31, v31
	v_fmac_f32_e32 v36, s2, v28
	v_add_f32_e32 v30, v30, v32
	v_mul_f32_e32 v31, v35, v35
	v_mul_f32_e32 v32, v37, v37
	v_fmac_f32_e32 v31, v33, v33
	v_fmac_f32_e32 v32, v36, v36
	v_add_f32_e32 v31, v31, v32
	v_add_f32_e32 v30, v30, v31
	v_lshlrev_b32_e32 v31, 16, v74
	v_fmac_f32_e32 v31, s2, v22
	v_and_b32_e32 v22, 0xffff0000, v74
	v_and_b32_e32 v32, 0xffff0000, v75
	v_cvt_pk_bf16_f32 v28, v33, v35
	v_fmac_f32_e32 v22, s2, v23
	v_lshlrev_b32_e32 v23, 16, v75
	v_fmac_f32_e32 v32, s2, v25
	v_lshlrev_b32_e32 v33, 16, v76
	v_and_b32_e32 v34, 0xffff0000, v76
	v_cvt_pk_bf16_f32 v29, v36, v37
	v_fmac_f32_e32 v23, s2, v24
	v_fmac_f32_e32 v33, s2, v18
	v_fmac_f32_e32 v34, s2, v19
	v_and_b32_e32 v36, 0xffff0000, v77
	v_mul_f32_e32 v18, v22, v22
	v_mul_f32_e32 v19, v32, v32
	v_lshlrev_b32_e32 v35, 16, v77
	v_fmac_f32_e32 v36, s2, v21
	v_fmac_f32_e32 v18, v31, v31
	v_fmac_f32_e32 v19, v23, v23
	v_fmac_f32_e32 v35, s2, v20
	v_add_f32_e32 v18, v18, v19
	v_mul_f32_e32 v19, v34, v34
	v_mul_f32_e32 v20, v36, v36
	v_fmac_f32_e32 v19, v33, v33
	v_fmac_f32_e32 v20, v35, v35
	v_add_f32_e32 v19, v19, v20
	v_add_f32_e32 v18, v18, v19
	v_add_f32_e32 v21, v30, v18
	ds_bpermute_b32 v30, v138, v21
	v_lshl_add_u64 v[18:19], s[14:15], 0, v[100:101]
	v_lshl_add_u64 v[24:25], v[166:167], 1, v[18:19]
	global_store_dwordx4 v[24:25], v[26:29], off
	v_cvt_pk_bf16_f32 v20, v31, v22
	s_waitcnt lgkmcnt(0)
	v_add_f32_e32 v18, v21, v30
	ds_bpermute_b32 v19, v139, v18
	v_cvt_pk_bf16_f32 v21, v23, v32
	v_cvt_pk_bf16_f32 v22, v33, v34
	v_cvt_pk_bf16_f32 v23, v35, v36
	global_store_dwordx4 v[24:25], v[20:23], off offset:256
	s_and_saveexec_b64 s[10:11], s[0:1]
	s_cbranch_execz .LBB0_744
	v_lshlrev_b64 v[20:21], 6, v[96:97]
	v_lshl_add_u64 v[20:21], s[12:13], 0, v[20:21]
	v_lshl_add_u64 v[20:21], s[42:43], 2, v[20:21]
	s_lshl_b32 s46, s95, 2
	v_lshl_add_u64 v[20:21], v[20:21], 0, s[46:47]
	s_waitcnt lgkmcnt(0)
	v_add_f32_e32 v18, v18, v19
	global_store_dword v[20:21], v18, off
.LBB0_744:
	s_or_b64 exec, exec, s[10:11]
	v_lshlrev_b32_e32 v20, 16, v71
	v_lshlrev_b32_e32 v18, 16, v70
	s_waitcnt lgkmcnt(0)
	v_and_b32_e32 v19, 0xffff0000, v70
	v_fmac_f32_e32 v20, s2, v16
	v_and_b32_e32 v16, 0xffff0000, v71
	v_fmac_f32_e32 v18, s2, v14
	v_fmac_f32_e32 v19, s2, v15
	v_fmac_f32_e32 v16, s2, v17
	v_lshlrev_b32_e32 v17, 16, v72
	v_and_b32_e32 v21, 0xffff0000, v72
	v_lshl_add_u64 v[14:15], s[14:15], 0, v[98:99]
	v_fmac_f32_e32 v17, s2, v10
	v_fmac_f32_e32 v21, s2, v11
	v_lshlrev_b32_e32 v22, 16, v73
	v_and_b32_e32 v23, 0xffff0000, v73
	v_cvt_pk_bf16_f32 v10, v18, v19
	v_cvt_pk_bf16_f32 v11, v20, v16
	v_lshl_add_u64 v[14:15], v[166:167], 1, v[14:15]
	v_fmac_f32_e32 v22, s2, v12
	v_fmac_f32_e32 v23, s2, v13
	v_cvt_pk_bf16_f32 v12, v17, v21
	v_cvt_pk_bf16_f32 v13, v22, v23
	global_store_dwordx4 v[14:15], v[10:13], off
	s_nop 1
	v_mul_f32_e32 v10, v19, v19
	v_mul_f32_e32 v11, v16, v16
	v_fmac_f32_e32 v10, v18, v18
	v_fmac_f32_e32 v11, v20, v20
	v_add_f32_e32 v10, v10, v11
	v_mul_f32_e32 v11, v21, v21
	v_mul_f32_e32 v12, v23, v23
	v_fmac_f32_e32 v11, v17, v17
	v_fmac_f32_e32 v12, v22, v22
	v_add_f32_e32 v11, v11, v12
	v_add_f32_e32 v10, v10, v11
	v_lshlrev_b32_e32 v11, 16, v66
	v_fmac_f32_e32 v11, s2, v6
	v_and_b32_e32 v6, 0xffff0000, v66
	v_fmac_f32_e32 v6, s2, v7
	v_lshlrev_b32_e32 v7, 16, v67
	v_fmac_f32_e32 v7, s2, v8
	v_and_b32_e32 v8, 0xffff0000, v67
	v_fmac_f32_e32 v8, s2, v9
	v_lshlrev_b32_e32 v9, 16, v68
	v_and_b32_e32 v12, 0xffff0000, v68
	v_fmac_f32_e32 v9, s2, v2
	v_fmac_f32_e32 v12, s2, v3
	v_lshlrev_b32_e32 v13, 16, v69
	v_and_b32_e32 v16, 0xffff0000, v69
	v_cvt_pk_bf16_f32 v2, v11, v6
	v_cvt_pk_bf16_f32 v3, v7, v8
	v_fmac_f32_e32 v13, s2, v4
	v_fmac_f32_e32 v16, s2, v5
	v_cvt_pk_bf16_f32 v4, v9, v12
	v_cvt_pk_bf16_f32 v5, v13, v16
	global_store_dwordx4 v[14:15], v[2:5], off offset:256
	s_nop 1
	v_mul_f32_e32 v2, v6, v6
	v_mul_f32_e32 v3, v8, v8
	v_fmac_f32_e32 v2, v11, v11
	v_fmac_f32_e32 v3, v7, v7
	v_add_f32_e32 v2, v2, v3
	v_mul_f32_e32 v3, v12, v12
	v_mul_f32_e32 v4, v16, v16
	v_fmac_f32_e32 v3, v9, v9
	v_fmac_f32_e32 v4, v13, v13
	v_add_f32_e32 v3, v3, v4
	v_add_f32_e32 v2, v2, v3
	v_add_f32_e32 v2, v10, v2
	ds_bpermute_b32 v3, v138, v2
	s_waitcnt lgkmcnt(0)
	v_add_f32_e32 v2, v2, v3
	ds_bpermute_b32 v3, v139, v2
	s_and_saveexec_b64 s[10:11], s[0:1]
	s_cbranch_execz .LBB0_746
	v_lshlrev_b64 v[4:5], 6, v[94:95]
	v_lshl_add_u64 v[4:5], s[12:13], 0, v[4:5]
	v_lshl_add_u64 v[4:5], s[42:43], 2, v[4:5]
	s_lshl_b32 s46, s95, 2
	v_lshl_add_u64 v[4:5], v[4:5], 0, s[46:47]
	s_waitcnt lgkmcnt(0)
	v_add_f32_e32 v2, v2, v3
	global_store_dword v[4:5], v2, off
